# baseline (speedup 1.0000x reference)
.LBB0_678:
	s_setprio 2
	v_bfe_u32 v136, v182, 4, 1
	v_mul_u32_u24_e32 v136, 24, v136
	v_add_u32_e32 v136, v0, v136
	v_mov_b32_e32 v137, 0
	v_mul_f32_e32 v132, 0xbfb8aa3b, v126
	v_exp_f32_e32 v132, v132
	s_mul_hi_i32 s2, s20, 0x160000
	s_mul_i32 s20, s20, 0x160000
	s_add_u32 s22, s92, s20
	v_add_f32_e32 v132, 1.0, v132
	v_rcp_f32_e32 v132, v132
	s_addc_u32 s2, s93, s2
	s_lshl_b32 s20, s21, 7
	s_ashr_i32 s21, s20, 31
	v_mul_f32_e32 v126, v126, v132
	v_mul_f32_e32 v122, v122, v126
	v_mul_f32_e32 v126, 0xbfb8aa3b, v127
	v_exp_f32_e32 v126, v126
	s_lshl_b64 s[20:21], s[20:21], 1
	s_add_u32 s20, s22, s20
	s_addc_u32 s21, s2, s21
	v_add_f32_e32 v126, 1.0, v126
	v_rcp_f32_e32 v126, v126
	v_lshl_add_u64 v[130:131], s[20:21], 0, v[196:197]
	v_mul_f32_e32 v126, v127, v126
	v_mul_f32_e32 v123, v123, v126
	v_cvt_pk_bf16_f32 v122, v122, v123
	v_mul_f32_e32 v123, 0xbfb8aa3b, v128
	v_exp_f32_e32 v123, v123
	s_nop 0
	v_add_f32_e32 v123, 1.0, v123
	v_rcp_f32_e32 v123, v123
	s_nop 0
	v_mul_f32_e32 v123, v128, v123
	v_mul_f32_e32 v123, v124, v123
	v_mul_f32_e32 v124, 0xbfb8aa3b, v129
	v_exp_f32_e32 v124, v124
	s_nop 0
	v_add_f32_e32 v124, 1.0, v124
	v_rcp_f32_e32 v124, v124
	s_nop 0
	v_mul_f32_e32 v124, v129, v124
	v_mul_f32_e32 v124, v125, v124
	v_cvt_pk_bf16_f32 v123, v123, v124
	v_lshl_add_u64 v[134:135], v[130:131], 0, v[136:137]
	v_mul_f32_e32 v138, 0xbfb8aa3b, v118
	v_exp_f32_e32 v138, v138
	s_nop 0
	v_add_f32_e32 v138, 1.0, v138
	v_rcp_f32_e32 v138, v138
	s_nop 0
	v_mul_f32_e32 v118, v118, v138
	v_mul_f32_e32 v114, v114, v118
	v_mul_f32_e32 v118, 0xbfb8aa3b, v119
	v_exp_f32_e32 v118, v118
	s_nop 0
	v_add_f32_e32 v118, 1.0, v118
	v_rcp_f32_e32 v118, v118
	s_nop 0
	v_mul_f32_e32 v118, v119, v118
	v_mul_f32_e32 v115, v115, v118
	v_cvt_pk_bf16_f32 v124, v114, v115
	v_mul_f32_e32 v115, 0xbfb8aa3b, v120
	v_exp_f32_e32 v115, v115
	s_nop 0
	v_add_f32_e32 v115, 1.0, v115
	v_rcp_f32_e32 v115, v115
	s_nop 0
	v_mul_f32_e32 v115, v120, v115
	v_mul_f32_e32 v115, v116, v115
	v_mul_f32_e32 v116, 0xbfb8aa3b, v121
	v_exp_f32_e32 v116, v116
	s_nop 0
	v_add_f32_e32 v116, 1.0, v116
	v_rcp_f32_e32 v116, v116
	s_nop 0
	v_mul_f32_e32 v116, v121, v116
	v_mul_f32_e32 v116, v117, v116
	v_cvt_pk_bf16_f32 v125, v115, v116
	s_nop 1
	v_permlane16_swap_b32_e32 v122, v124
	v_permlane16_swap_b32_e32 v123, v125
	global_store_dwordx4 v[134:135], v[122:125], off
	v_mul_f32_e32 v116, 0xbfb8aa3b, v110
	v_exp_f32_e32 v116, v116
	v_lshl_add_u64 v[114:115], s[20:21], 0, v[198:199]
	v_add_f32_e32 v116, 1.0, v116
	v_rcp_f32_e32 v116, v116
	s_nop 0
	v_mul_f32_e32 v110, v110, v116
	v_mul_f32_e32 v106, v106, v110
	v_mul_f32_e32 v110, 0xbfb8aa3b, v111
	v_exp_f32_e32 v110, v110
	s_nop 0
	v_add_f32_e32 v110, 1.0, v110
	v_rcp_f32_e32 v110, v110
	s_nop 0
	v_mul_f32_e32 v110, v111, v110
	v_mul_f32_e32 v107, v107, v110
	v_cvt_pk_bf16_f32 v106, v106, v107
	v_mul_f32_e32 v107, 0xbfb8aa3b, v112
	v_exp_f32_e32 v107, v107
	s_nop 0
	v_add_f32_e32 v107, 1.0, v107
	v_rcp_f32_e32 v107, v107
	s_nop 0
	v_mul_f32_e32 v107, v112, v107
	v_mul_f32_e32 v107, v108, v107
	v_mul_f32_e32 v108, 0xbfb8aa3b, v113
	v_exp_f32_e32 v108, v108
	s_nop 0
	v_add_f32_e32 v108, 1.0, v108
	v_rcp_f32_e32 v108, v108
	s_nop 0
	v_mul_f32_e32 v108, v113, v108
	v_mul_f32_e32 v108, v109, v108
	v_cvt_pk_bf16_f32 v107, v107, v108
	v_lshl_add_u64 v[134:135], v[114:115], 0, v[136:137]
	v_mul_f32_e32 v138, 0xbfb8aa3b, v102
	v_exp_f32_e32 v138, v138
	s_nop 0
	v_add_f32_e32 v138, 1.0, v138
	v_rcp_f32_e32 v138, v138
	s_nop 0
	v_mul_f32_e32 v102, v102, v138
	v_mul_f32_e32 v98, v98, v102
	v_mul_f32_e32 v102, 0xbfb8aa3b, v103
	v_exp_f32_e32 v102, v102
	s_nop 0
	v_add_f32_e32 v102, 1.0, v102
	v_rcp_f32_e32 v102, v102
	s_nop 0
	v_mul_f32_e32 v102, v103, v102
	v_mul_f32_e32 v99, v99, v102
	v_cvt_pk_bf16_f32 v108, v98, v99
	v_mul_f32_e32 v99, 0xbfb8aa3b, v104
	v_exp_f32_e32 v99, v99
	s_nop 0
	v_add_f32_e32 v99, 1.0, v99
	v_rcp_f32_e32 v99, v99
	s_nop 0
	v_mul_f32_e32 v99, v104, v99
	v_mul_f32_e32 v99, v100, v99
	v_mul_f32_e32 v100, 0xbfb8aa3b, v105
	v_exp_f32_e32 v100, v100
	s_nop 0
	v_add_f32_e32 v100, 1.0, v100
	v_rcp_f32_e32 v100, v100
	s_nop 0
	v_mul_f32_e32 v100, v105, v100
	v_mul_f32_e32 v100, v101, v100
	v_cvt_pk_bf16_f32 v109, v99, v100
	s_nop 1
	v_permlane16_swap_b32_e32 v106, v108
	v_permlane16_swap_b32_e32 v107, v109
	global_store_dwordx4 v[134:135], v[106:109], off
	v_mul_f32_e32 v100, 0xbfb8aa3b, v94
	v_exp_f32_e32 v100, v100
	v_lshl_add_u64 v[98:99], s[20:21], 0, v[200:201]
	v_add_f32_e32 v100, 1.0, v100
	v_rcp_f32_e32 v100, v100
	s_nop 0
	v_mul_f32_e32 v94, v94, v100
	v_mul_f32_e32 v90, v90, v94
	v_mul_f32_e32 v94, 0xbfb8aa3b, v95
	v_exp_f32_e32 v94, v94
	s_nop 0
	v_add_f32_e32 v94, 1.0, v94
	v_rcp_f32_e32 v94, v94
	s_nop 0
	v_mul_f32_e32 v94, v95, v94
	v_mul_f32_e32 v91, v91, v94
	v_cvt_pk_bf16_f32 v90, v90, v91
	v_mul_f32_e32 v91, 0xbfb8aa3b, v96
	v_exp_f32_e32 v91, v91
	s_nop 0
	v_add_f32_e32 v91, 1.0, v91
	v_rcp_f32_e32 v91, v91
	s_nop 0
	v_mul_f32_e32 v91, v96, v91
	v_mul_f32_e32 v91, v92, v91
	v_mul_f32_e32 v92, 0xbfb8aa3b, v97
	v_exp_f32_e32 v92, v92
	s_nop 0
	v_add_f32_e32 v92, 1.0, v92
	v_rcp_f32_e32 v92, v92
	s_nop 0
	v_mul_f32_e32 v92, v97, v92
	v_mul_f32_e32 v92, v93, v92
	v_cvt_pk_bf16_f32 v91, v91, v92
	v_lshl_add_u64 v[134:135], v[98:99], 0, v[136:137]
	v_mul_f32_e32 v138, 0xbfb8aa3b, v86
	v_exp_f32_e32 v138, v138
	s_nop 0
	v_add_f32_e32 v138, 1.0, v138
	v_rcp_f32_e32 v138, v138
	s_nop 0
	v_mul_f32_e32 v86, v86, v138
	v_mul_f32_e32 v82, v82, v86
	v_mul_f32_e32 v86, 0xbfb8aa3b, v87
	v_exp_f32_e32 v86, v86
	s_nop 0
	v_add_f32_e32 v86, 1.0, v86
	v_rcp_f32_e32 v86, v86
	s_nop 0
	v_mul_f32_e32 v86, v87, v86
	v_mul_f32_e32 v83, v83, v86
	v_cvt_pk_bf16_f32 v92, v82, v83
	v_mul_f32_e32 v83, 0xbfb8aa3b, v88
	v_exp_f32_e32 v83, v83
	s_nop 0
	v_add_f32_e32 v83, 1.0, v83
	v_rcp_f32_e32 v83, v83
	s_nop 0
	v_mul_f32_e32 v83, v88, v83
	v_mul_f32_e32 v83, v84, v83
	v_mul_f32_e32 v84, 0xbfb8aa3b, v89
	v_exp_f32_e32 v84, v84
	s_nop 0
	v_add_f32_e32 v84, 1.0, v84
	v_rcp_f32_e32 v84, v84
	s_nop 0
	v_mul_f32_e32 v84, v89, v84
	v_mul_f32_e32 v84, v85, v84
	v_cvt_pk_bf16_f32 v93, v83, v84
	s_nop 1
	v_permlane16_swap_b32_e32 v90, v92
	v_permlane16_swap_b32_e32 v91, v93
	global_store_dwordx4 v[134:135], v[90:93], off
	v_mul_f32_e32 v84, 0xbfb8aa3b, v78
	v_exp_f32_e32 v84, v84
	v_lshl_add_u64 v[82:83], s[20:21], 0, v[202:203]
	v_add_f32_e32 v84, 1.0, v84
	v_rcp_f32_e32 v84, v84
	s_nop 0
	v_mul_f32_e32 v78, v78, v84
	v_mul_f32_e32 v74, v74, v78
	v_mul_f32_e32 v78, 0xbfb8aa3b, v79
	v_exp_f32_e32 v78, v78
	s_nop 0
	v_add_f32_e32 v78, 1.0, v78
	v_rcp_f32_e32 v78, v78
	s_nop 0
	v_mul_f32_e32 v78, v79, v78
	v_mul_f32_e32 v75, v75, v78
	v_cvt_pk_bf16_f32 v74, v74, v75
	v_mul_f32_e32 v75, 0xbfb8aa3b, v80
	v_exp_f32_e32 v75, v75
	s_nop 0
	v_add_f32_e32 v75, 1.0, v75
	v_rcp_f32_e32 v75, v75
	s_nop 0
	v_mul_f32_e32 v75, v80, v75
	v_mul_f32_e32 v75, v76, v75
	v_mul_f32_e32 v76, 0xbfb8aa3b, v81
	v_exp_f32_e32 v76, v76
	s_nop 0
	v_add_f32_e32 v76, 1.0, v76
	v_rcp_f32_e32 v76, v76
	s_nop 0
	v_mul_f32_e32 v76, v81, v76
	v_mul_f32_e32 v76, v77, v76
	v_cvt_pk_bf16_f32 v75, v75, v76
	v_lshl_add_u64 v[134:135], v[82:83], 0, v[136:137]
	v_mul_f32_e32 v138, 0xbfb8aa3b, v70
	v_exp_f32_e32 v138, v138
	s_nop 0
	v_add_f32_e32 v138, 1.0, v138
	v_rcp_f32_e32 v138, v138
	s_nop 0
	v_mul_f32_e32 v70, v70, v138
	v_mul_f32_e32 v66, v66, v70
	v_mul_f32_e32 v70, 0xbfb8aa3b, v71
	v_exp_f32_e32 v70, v70
	s_nop 0
	v_add_f32_e32 v70, 1.0, v70
	v_rcp_f32_e32 v70, v70
	s_nop 0
	v_mul_f32_e32 v70, v71, v70
	v_mul_f32_e32 v67, v67, v70
	v_cvt_pk_bf16_f32 v76, v66, v67
	v_mul_f32_e32 v67, 0xbfb8aa3b, v72
	v_exp_f32_e32 v67, v67
	s_nop 0
	v_add_f32_e32 v67, 1.0, v67
	v_rcp_f32_e32 v67, v67
	s_nop 0
	v_mul_f32_e32 v67, v72, v67
	v_mul_f32_e32 v67, v68, v67
	v_mul_f32_e32 v68, 0xbfb8aa3b, v73
	v_exp_f32_e32 v68, v68
	s_nop 0
	v_add_f32_e32 v68, 1.0, v68
	v_rcp_f32_e32 v68, v68
	s_nop 0
	v_mul_f32_e32 v68, v73, v68
	v_mul_f32_e32 v68, v69, v68
	v_cvt_pk_bf16_f32 v77, v67, v68
	s_nop 1
	v_permlane16_swap_b32_e32 v74, v76
	v_permlane16_swap_b32_e32 v75, v77
	global_store_dwordx4 v[134:135], v[74:77], off
	v_mul_f32_e32 v68, 0xbfb8aa3b, v62
	v_exp_f32_e32 v68, v68
	v_lshl_add_u64 v[66:67], s[20:21], 0, v[204:205]
	v_add_f32_e32 v68, 1.0, v68
	v_rcp_f32_e32 v68, v68
	s_nop 0
	v_mul_f32_e32 v62, v62, v68
	v_mul_f32_e32 v58, v58, v62
	v_mul_f32_e32 v62, 0xbfb8aa3b, v63
	v_exp_f32_e32 v62, v62
	s_nop 0
	v_add_f32_e32 v62, 1.0, v62
	v_rcp_f32_e32 v62, v62
	s_nop 0
	v_mul_f32_e32 v62, v63, v62
	v_mul_f32_e32 v59, v59, v62
	v_cvt_pk_bf16_f32 v58, v58, v59
	v_mul_f32_e32 v59, 0xbfb8aa3b, v64
	v_exp_f32_e32 v59, v59
	s_nop 0
	v_add_f32_e32 v59, 1.0, v59
	v_rcp_f32_e32 v59, v59
	s_nop 0
	v_mul_f32_e32 v59, v64, v59
	v_mul_f32_e32 v59, v60, v59
	v_mul_f32_e32 v60, 0xbfb8aa3b, v65
	v_exp_f32_e32 v60, v60
	s_nop 0
	v_add_f32_e32 v60, 1.0, v60
	v_rcp_f32_e32 v60, v60
	s_nop 0
	v_mul_f32_e32 v60, v65, v60
	v_mul_f32_e32 v60, v61, v60
	v_cvt_pk_bf16_f32 v59, v59, v60
	v_lshl_add_u64 v[134:135], v[66:67], 0, v[136:137]
	v_mul_f32_e32 v138, 0xbfb8aa3b, v54
	v_exp_f32_e32 v138, v138
	s_nop 0
	v_add_f32_e32 v138, 1.0, v138
	v_rcp_f32_e32 v138, v138
	s_nop 0
	v_mul_f32_e32 v54, v54, v138
	v_mul_f32_e32 v50, v50, v54
	v_mul_f32_e32 v54, 0xbfb8aa3b, v55
	v_exp_f32_e32 v54, v54
	s_nop 0
	v_add_f32_e32 v54, 1.0, v54
	v_rcp_f32_e32 v54, v54
	s_nop 0
	v_mul_f32_e32 v54, v55, v54
	v_mul_f32_e32 v51, v51, v54
	v_cvt_pk_bf16_f32 v60, v50, v51
	v_mul_f32_e32 v51, 0xbfb8aa3b, v56
	v_exp_f32_e32 v51, v51
	s_nop 0
	v_add_f32_e32 v51, 1.0, v51
	v_rcp_f32_e32 v51, v51
	s_nop 0
	v_mul_f32_e32 v51, v56, v51
	v_mul_f32_e32 v51, v52, v51
	v_mul_f32_e32 v52, 0xbfb8aa3b, v57
	v_exp_f32_e32 v52, v52
	s_nop 0
	v_add_f32_e32 v52, 1.0, v52
	v_rcp_f32_e32 v52, v52
	s_nop 0
	v_mul_f32_e32 v52, v57, v52
	v_mul_f32_e32 v52, v53, v52
	v_cvt_pk_bf16_f32 v61, v51, v52
	s_nop 1
	v_permlane16_swap_b32_e32 v58, v60
	v_permlane16_swap_b32_e32 v59, v61
	global_store_dwordx4 v[134:135], v[58:61], off
	v_mul_f32_e32 v52, 0xbfb8aa3b, v46
	v_exp_f32_e32 v52, v52
	v_lshl_add_u64 v[50:51], s[20:21], 0, v[206:207]
	v_add_f32_e32 v52, 1.0, v52
	v_rcp_f32_e32 v52, v52
	s_nop 0
	v_mul_f32_e32 v46, v46, v52
	v_mul_f32_e32 v42, v42, v46
	v_mul_f32_e32 v46, 0xbfb8aa3b, v47
	v_exp_f32_e32 v46, v46
	s_nop 0
	v_add_f32_e32 v46, 1.0, v46
	v_rcp_f32_e32 v46, v46
	s_nop 0
	v_mul_f32_e32 v46, v47, v46
	v_mul_f32_e32 v43, v43, v46
	v_cvt_pk_bf16_f32 v42, v42, v43
	v_mul_f32_e32 v43, 0xbfb8aa3b, v48
	v_exp_f32_e32 v43, v43
	s_nop 0
	v_add_f32_e32 v43, 1.0, v43
	v_rcp_f32_e32 v43, v43
	s_nop 0
	v_mul_f32_e32 v43, v48, v43
	v_mul_f32_e32 v43, v44, v43
	v_mul_f32_e32 v44, 0xbfb8aa3b, v49
	v_exp_f32_e32 v44, v44
; template <class DescFn, class EpiFn>
; __device__ __forceinline__ void gemm_phase(int nM, int nN, DescFn dfn, EpiFn efn) {
;     ...
;     efn(cpm, cpn)(acc, wr, wc, fr, fq);
;     if (!more) break;
	s_nop 0
	v_add_f32_e32 v44, 1.0, v44
	v_rcp_f32_e32 v44, v44
	s_nop 0
	v_mul_f32_e32 v44, v49, v44
	v_mul_f32_e32 v44, v45, v44
	v_cvt_pk_bf16_f32 v43, v43, v44
	v_lshl_add_u64 v[134:135], v[50:51], 0, v[136:137]
	v_mul_f32_e32 v138, 0xbfb8aa3b, v38
	v_exp_f32_e32 v138, v138
	s_nop 0
	v_add_f32_e32 v138, 1.0, v138
	v_rcp_f32_e32 v138, v138
	s_nop 0
	v_mul_f32_e32 v38, v38, v138
	v_mul_f32_e32 v34, v34, v38
	v_mul_f32_e32 v38, 0xbfb8aa3b, v39
	v_exp_f32_e32 v38, v38
	s_nop 0
	v_add_f32_e32 v38, 1.0, v38
	v_rcp_f32_e32 v38, v38
	s_nop 0
	v_mul_f32_e32 v38, v39, v38
	v_mul_f32_e32 v35, v35, v38
	v_cvt_pk_bf16_f32 v44, v34, v35
	v_mul_f32_e32 v35, 0xbfb8aa3b, v40
	v_exp_f32_e32 v35, v35
	s_nop 0
	v_add_f32_e32 v35, 1.0, v35
	v_rcp_f32_e32 v35, v35
	s_nop 0
	v_mul_f32_e32 v35, v40, v35
	v_mul_f32_e32 v35, v36, v35
	v_mul_f32_e32 v36, 0xbfb8aa3b, v41
	v_exp_f32_e32 v36, v36
	s_nop 0
	v_add_f32_e32 v36, 1.0, v36
	v_rcp_f32_e32 v36, v36
	s_nop 0
	v_mul_f32_e32 v36, v41, v36
	v_mul_f32_e32 v36, v37, v36
	v_cvt_pk_bf16_f32 v45, v35, v36
	s_nop 1
	v_permlane16_swap_b32_e32 v42, v44
	v_permlane16_swap_b32_e32 v43, v45
	global_store_dwordx4 v[134:135], v[42:45], off
	v_mul_f32_e32 v36, 0xbfb8aa3b, v30
	v_exp_f32_e32 v36, v36
	v_lshl_add_u64 v[34:35], s[20:21], 0, v[208:209]
	v_add_f32_e32 v36, 1.0, v36
	v_rcp_f32_e32 v36, v36
	s_nop 0
	v_mul_f32_e32 v30, v30, v36
	v_mul_f32_e32 v26, v26, v30
	v_mul_f32_e32 v30, 0xbfb8aa3b, v31
	v_exp_f32_e32 v30, v30
	s_nop 0
	v_add_f32_e32 v30, 1.0, v30
	v_rcp_f32_e32 v30, v30
	s_nop 0
	v_mul_f32_e32 v30, v31, v30
	v_mul_f32_e32 v27, v27, v30
	v_cvt_pk_bf16_f32 v26, v26, v27
	v_mul_f32_e32 v27, 0xbfb8aa3b, v32
	v_exp_f32_e32 v27, v27
	s_nop 0
	v_add_f32_e32 v27, 1.0, v27
	v_rcp_f32_e32 v27, v27
	s_nop 0
	v_mul_f32_e32 v27, v32, v27
	v_mul_f32_e32 v27, v28, v27
	v_mul_f32_e32 v28, 0xbfb8aa3b, v33
	v_exp_f32_e32 v28, v28
	s_nop 0
	v_add_f32_e32 v28, 1.0, v28
	v_rcp_f32_e32 v28, v28
	s_nop 0
	v_mul_f32_e32 v28, v33, v28
	v_mul_f32_e32 v28, v29, v28
	v_cvt_pk_bf16_f32 v27, v27, v28
	v_lshl_add_u64 v[134:135], v[34:35], 0, v[136:137]
	v_mul_f32_e32 v138, 0xbfb8aa3b, v22
	v_exp_f32_e32 v138, v138
	s_nop 0
	v_add_f32_e32 v138, 1.0, v138
	v_rcp_f32_e32 v138, v138
	s_nop 0
	v_mul_f32_e32 v22, v22, v138
	v_mul_f32_e32 v18, v18, v22
	v_mul_f32_e32 v22, 0xbfb8aa3b, v23
	v_exp_f32_e32 v22, v22
	s_nop 0
	v_add_f32_e32 v22, 1.0, v22
	v_rcp_f32_e32 v22, v22
	s_nop 0
	v_mul_f32_e32 v22, v23, v22
	v_mul_f32_e32 v19, v19, v22
	v_cvt_pk_bf16_f32 v28, v18, v19
	v_mul_f32_e32 v19, 0xbfb8aa3b, v24
	v_exp_f32_e32 v19, v19
	s_nop 0
	v_add_f32_e32 v19, 1.0, v19
	v_rcp_f32_e32 v19, v19
	s_nop 0
	v_mul_f32_e32 v19, v24, v19
	v_mul_f32_e32 v19, v20, v19
	v_mul_f32_e32 v20, 0xbfb8aa3b, v25
	v_exp_f32_e32 v20, v20
	s_nop 0
	v_add_f32_e32 v20, 1.0, v20
	v_rcp_f32_e32 v20, v20
	s_nop 0
	v_mul_f32_e32 v20, v25, v20
	v_mul_f32_e32 v20, v21, v20
	v_cvt_pk_bf16_f32 v29, v19, v20
	s_nop 1
	v_permlane16_swap_b32_e32 v26, v28
	v_permlane16_swap_b32_e32 v27, v29
	global_store_dwordx4 v[134:135], v[26:29], off
	v_mul_f32_e32 v20, 0xbfb8aa3b, v14
	v_exp_f32_e32 v20, v20
	v_lshl_add_u64 v[18:19], s[20:21], 0, v[210:211]
	v_add_f32_e32 v20, 1.0, v20
	v_rcp_f32_e32 v20, v20
	s_nop 0
	v_mul_f32_e32 v14, v14, v20
	v_mul_f32_e32 v10, v10, v14
	v_mul_f32_e32 v14, 0xbfb8aa3b, v15
	v_exp_f32_e32 v14, v14
	s_nop 0
	v_add_f32_e32 v14, 1.0, v14
	v_rcp_f32_e32 v14, v14
	s_nop 0
	v_mul_f32_e32 v14, v15, v14
	v_mul_f32_e32 v11, v11, v14
	v_cvt_pk_bf16_f32 v10, v10, v11
	v_mul_f32_e32 v11, 0xbfb8aa3b, v16
	v_exp_f32_e32 v11, v11
	s_nop 0
	v_add_f32_e32 v11, 1.0, v11
	v_rcp_f32_e32 v11, v11
	s_nop 0
	v_mul_f32_e32 v11, v16, v11
	v_mul_f32_e32 v11, v12, v11
	v_mul_f32_e32 v12, 0xbfb8aa3b, v17
	v_exp_f32_e32 v12, v12
	s_nop 0
	v_add_f32_e32 v12, 1.0, v12
	v_rcp_f32_e32 v12, v12
	s_nop 0
	v_mul_f32_e32 v12, v17, v12
	v_mul_f32_e32 v12, v13, v12
	v_cvt_pk_bf16_f32 v11, v11, v12
	v_lshl_add_u64 v[134:135], v[18:19], 0, v[136:137]
	v_mul_f32_e32 v138, 0xbfb8aa3b, v6
	v_exp_f32_e32 v138, v138
	s_nop 0
	v_add_f32_e32 v138, 1.0, v138
	v_rcp_f32_e32 v138, v138
	s_nop 0
	v_mul_f32_e32 v6, v6, v138
	v_mul_f32_e32 v2, v2, v6
	v_mul_f32_e32 v6, 0xbfb8aa3b, v7
	v_exp_f32_e32 v6, v6
	s_nop 0
	v_add_f32_e32 v6, 1.0, v6
	v_rcp_f32_e32 v6, v6
	s_nop 0
	v_mul_f32_e32 v6, v7, v6
	v_mul_f32_e32 v3, v3, v6
	v_cvt_pk_bf16_f32 v12, v2, v3
	v_mul_f32_e32 v3, 0xbfb8aa3b, v8
	v_exp_f32_e32 v3, v3
	s_nop 0
	v_add_f32_e32 v3, 1.0, v3
	v_rcp_f32_e32 v3, v3
	s_nop 0
	v_mul_f32_e32 v3, v8, v3
	v_mul_f32_e32 v3, v4, v3
	v_mul_f32_e32 v4, 0xbfb8aa3b, v9
	v_exp_f32_e32 v4, v4
	s_nop 0
	v_add_f32_e32 v4, 1.0, v4
	v_rcp_f32_e32 v4, v4
	s_nop 0
	v_mul_f32_e32 v4, v9, v4
	v_mul_f32_e32 v4, v5, v4
	v_cvt_pk_bf16_f32 v13, v3, v4
	s_nop 1
	v_permlane16_swap_b32_e32 v10, v12
	v_permlane16_swap_b32_e32 v11, v13
	global_store_dwordx4 v[134:135], v[10:13], off
	s_setprio 0
	s_andn2_b64 vcc, exec, s[18:19]
	s_mov_b64 s[18:19], -1
	s_cbranch_vccnz .LBB0_657
	s_mov_b64 s[18:19], 0
	s_branch .LBB0_657
